# hgrn pass-3 chunk-prefix loads batched 4 chunks deep; rmsnorm row loop issues all four row loads up front
# speedup vs baseline: 1.0829x; 1.0076x over previous
.LBB0_185:
	v_ashrrev_i32_e32 v17, 31, v16
	v_lshlrev_b64 v[28:29], 11, v[16:17]
	v_lshl_add_u64 v[44:45], s[14:15], 0, v[28:29]
	v_lshlrev_b64 v[28:29], 12, v[16:17]
	v_lshl_add_u64 v[40:41], v[18:19], 0, v[28:29]
	global_load_dwordx4 v[28:31], v[40:41], off offset:2048
	global_load_dwordx4 v[32:35], v[40:41], off offset:3072
	global_load_dwordx4 v[250:253], v[40:41], off
	global_load_dwordx4 v[246:249], v[40:41], off offset:1024
	v_lshl_add_u64 v[52:53], v[44:45], 0, v[64:65]
	v_add_u32_e32 v16, s81, v16
	s_waitcnt vmcnt(2)
	v_mov_b32_e32 v38, v29
	s_waitcnt vmcnt(2)
	v_mov_b32_e32 v39, v33
	v_mov_b32_e32 v36, v28
	v_mov_b32_e32 v37, v32
	v_pk_mul_f32 v[38:39], v[38:39], v[38:39]
	s_nop 0
	v_pk_fma_f32 v[36:37], v[36:37], v[36:37], v[38:39]
	v_mov_b32_e32 v38, v30
	v_mov_b32_e32 v39, v34
	v_pk_fma_f32 v[36:37], v[38:39], v[38:39], v[36:37]
	v_mov_b32_e32 v38, v31
	v_mov_b32_e32 v39, v35
	v_pk_fma_f32 v[46:47], v[38:39], v[38:39], v[36:37]
	s_waitcnt vmcnt(1)
	v_pk_mul_f32 v[50:51], v[250:251], v[250:251]
	v_pk_mul_f32 v[48:49], v[252:253], v[252:253]
	v_add_f32_e32 v50, v50, v51
	v_add_f32_e32 v48, v50, v48
	v_add_f32_e32 v48, v48, v49
	s_waitcnt vmcnt(0)
	v_pk_mul_f32 v[56:57], v[246:247], v[246:247]
	v_pk_mul_f32 v[54:55], v[248:249], v[248:249]
	v_add_f32_e32 v17, v56, v57
	v_add_f32_e32 v17, v17, v54
	v_add_f32_e32 v17, v17, v55
	v_add_f32_e32 v17, v48, v17
	v_add_f32_e32 v17, v17, v46
	v_add_f32_e32 v17, v17, v47
	s_nop 1
	v_add_f32_dpp v17, v17, v17 quad_perm:[1,0,3,2] row_mask:0xf bank_mask:0xf bound_ctrl:1
	s_nop 1
	v_add_f32_dpp v17, v17, v17 quad_perm:[2,3,0,1] row_mask:0xf bank_mask:0xf bound_ctrl:1
	s_nop 1
	v_add_f32_dpp v17, v17, v17 row_half_mirror row_mask:0xf bank_mask:0xf bound_ctrl:1
	s_nop 1
	v_add_f32_dpp v17, v17, v17 row_mirror row_mask:0xf bank_mask:0xf bound_ctrl:1
	ds_bpermute_b32 v46, v26, v17
	s_waitcnt lgkmcnt(0)
	v_add_f32_e32 v17, v17, v46
	ds_bpermute_b32 v46, v27, v17
	s_waitcnt lgkmcnt(0)
	v_add_f32_e32 v17, v17, v46
	v_fmamk_f32 v17, v17, 0x3a800000, v171
	v_cmp_gt_f32_e32 vcc, s3, v17
	v_mul_f32_e32 v46, 0x4f800000, v17
	s_nop 0
	v_cndmask_b32_e32 v17, v17, v46, vcc
	v_sqrt_f32_e32 v46, v17
	s_nop 0
	v_add_u32_e32 v47, -1, v46
	v_fma_f32 v48, -v47, v46, v17
	v_cmp_ge_f32_e64 s[0:1], 0, v48
	v_add_u32_e32 v48, 1, v46
	s_nop 0
	v_cndmask_b32_e64 v47, v46, v47, s[0:1]
	v_fma_f32 v46, -v48, v46, v17
	v_cmp_lt_f32_e64 s[0:1], 0, v46
	s_nop 1
	v_cndmask_b32_e64 v46, v47, v48, s[0:1]
	v_mul_f32_e32 v47, 0x37800000, v46
	v_cndmask_b32_e32 v46, v46, v47, vcc
	v_cmp_class_f32_e32 vcc, v17, v172
	s_nop 1
	v_cndmask_b32_e32 v17, v46, v17, vcc
	v_div_scale_f32 v46, s[0:1], v17, v17, 1.0
	v_rcp_f32_e32 v47, v46
	s_mov_b32 s0, 0xffff
	v_fma_f32 v48, -v46, v47, 1.0
	v_fmac_f32_e32 v47, v48, v47
	v_div_scale_f32 v48, vcc, 1.0, v17, 1.0
	v_mul_f32_e32 v49, v48, v47
	v_fma_f32 v50, -v46, v49, v48
	v_fmac_f32_e32 v49, v50, v47
	v_fma_f32 v46, -v46, v49, v48
	v_div_fmas_f32 v46, v46, v47, v49
	v_div_fixup_f32 v46, v46, v17, 1.0
	v_pk_mul_f32 v[250:251], v[250:251], v[46:47] op_sel_hi:[1,0]
	v_pk_mul_f32 v[252:253], v[252:253], v[46:47] op_sel_hi:[1,0]
	v_pk_mul_f32 v[28:29], v[28:29], v[46:47] op_sel_hi:[1,0]
	v_pk_mul_f32 v[30:31], v[30:31], v[46:47] op_sel_hi:[1,0]
	v_pk_mul_f32 v[250:251], v[0:1], v[250:251]
	v_pk_mul_f32 v[252:253], v[2:3], v[252:253]
	v_pk_mul_f32 v[28:29], v[8:9], v[28:29]
	v_pk_mul_f32 v[30:31], v[10:11], v[30:31]
	v_cvt_pk_bf16_f32 v250, v250, v251
	v_cvt_pk_bf16_f32 v251, v252, v253
	v_cvt_pk_bf16_f32 v28, v28, v29
	v_cvt_pk_bf16_f32 v29, v30, v31
	v_lshl_add_u64 v[30:31], v[44:45], 0, v[22:23]
	global_store_dwordx2 v[52:53], v[250:251], off
	v_pk_mul_f32 v[250:251], v[246:247], v[46:47] op_sel_hi:[1,0]
	v_pk_mul_f32 v[252:253], v[248:249], v[46:47] op_sel_hi:[1,0]
	global_store_dwordx2 v[30:31], v[28:29], off
	v_pk_mul_f32 v[28:29], v[32:33], v[46:47] op_sel_hi:[1,0]
	v_pk_mul_f32 v[30:31], v[34:35], v[46:47] op_sel_hi:[1,0]
	v_pk_mul_f32 v[250:251], v[4:5], v[250:251]
	v_pk_mul_f32 v[252:253], v[6:7], v[252:253]
	v_pk_mul_f32 v[28:29], v[12:13], v[28:29]
	v_pk_mul_f32 v[30:31], v[14:15], v[30:31]
	v_cmp_lt_i32_e32 vcc, s0, v16
	v_cvt_pk_bf16_f32 v250, v250, v251
	v_cvt_pk_bf16_f32 v251, v252, v253
	v_lshl_add_u64 v[252:253], v[44:45], 0, v[20:21]
	v_cvt_pk_bf16_f32 v28, v28, v29
	v_cvt_pk_bf16_f32 v29, v30, v31
	v_lshl_add_u64 v[30:31], v[44:45], 0, v[24:25]
	s_or_b64 s[28:29], vcc, s[28:29]
	global_store_dwordx2 v[252:253], v[250:251], off
	global_store_dwordx2 v[30:31], v[28:29], off
	s_andn2_b64 exec, exec, s[28:29]
	s_cbranch_execnz .LBB0_185

.LBB0_558:
	v_ashrrev_i32_e32 v25, 31, v24
	v_lshlrev_b64 v[16:17], 11, v[24:25]
	v_lshl_add_u64 v[34:35], s[14:15], 0, v[16:17]
	v_lshlrev_b64 v[16:17], 12, v[24:25]
	v_lshl_add_u64 v[44:45], v[26:27], 0, v[16:17]
	global_load_dwordx4 v[20:23], v[44:45], off offset:2048
	global_load_dwordx4 v[16:19], v[44:45], off offset:3072
	global_load_dwordx4 v[250:253], v[44:45], off
	global_load_dwordx4 v[246:249], v[44:45], off offset:1024
	v_lshl_add_u64 v[54:55], v[34:35], 0, v[64:65]
	v_add_u32_e32 v24, s81, v24
	s_waitcnt vmcnt(2)
	v_mov_b32_e32 v42, v21
	s_waitcnt vmcnt(2)
	v_mov_b32_e32 v43, v17
	v_mov_b32_e32 v40, v20
	v_mov_b32_e32 v41, v16
	v_pk_mul_f32 v[42:43], v[42:43], v[42:43]
	s_nop 0
	v_pk_fma_f32 v[40:41], v[40:41], v[40:41], v[42:43]
	v_mov_b32_e32 v42, v22
	v_mov_b32_e32 v43, v18
	v_pk_fma_f32 v[40:41], v[42:43], v[42:43], v[40:41]
	v_mov_b32_e32 v42, v23
	v_mov_b32_e32 v43, v19
	v_pk_fma_f32 v[48:49], v[42:43], v[42:43], v[40:41]
	s_waitcnt vmcnt(1)
	v_pk_mul_f32 v[52:53], v[250:251], v[250:251]
	v_pk_mul_f32 v[50:51], v[252:253], v[252:253]
	v_add_f32_e32 v29, v52, v53
	v_add_f32_e32 v29, v29, v50
	v_add_f32_e32 v29, v29, v51
	s_waitcnt vmcnt(0)
	v_pk_mul_f32 v[58:59], v[246:247], v[246:247]
	v_pk_mul_f32 v[56:57], v[248:249], v[248:249]
	v_add_f32_e32 v25, v58, v59
	v_add_f32_e32 v25, v25, v56
	v_add_f32_e32 v25, v25, v57
	v_add_f32_e32 v25, v29, v25
	v_add_f32_e32 v25, v25, v48
	v_add_f32_e32 v25, v25, v49
	s_nop 1
	v_add_f32_dpp v25, v25, v25 quad_perm:[1,0,3,2] row_mask:0xf bank_mask:0xf bound_ctrl:1
	s_nop 1
	v_add_f32_dpp v25, v25, v25 quad_perm:[2,3,0,1] row_mask:0xf bank_mask:0xf bound_ctrl:1
	s_nop 1
	v_add_f32_dpp v25, v25, v25 row_half_mirror row_mask:0xf bank_mask:0xf bound_ctrl:1
	s_nop 1
	v_add_f32_dpp v25, v25, v25 row_mirror row_mask:0xf bank_mask:0xf bound_ctrl:1
	ds_bpermute_b32 v29, v37, v25
	s_waitcnt lgkmcnt(0)
	v_add_f32_e32 v25, v25, v29
	ds_bpermute_b32 v29, v38, v25
	s_waitcnt lgkmcnt(0)
	v_add_f32_e32 v25, v25, v29
	v_fmamk_f32 v25, v25, 0x3a800000, v171
	v_cmp_gt_f32_e32 vcc, s3, v25
	v_mul_f32_e32 v29, 0x4f800000, v25
	s_nop 0
	v_cndmask_b32_e32 v25, v25, v29, vcc
	v_sqrt_f32_e32 v29, v25
	s_nop 0
	v_add_u32_e32 v31, -1, v29
	v_fma_f32 v33, -v31, v29, v25
	v_cmp_ge_f32_e64 s[0:1], 0, v33
	v_add_u32_e32 v33, 1, v29
	s_nop 0
	v_cndmask_b32_e64 v31, v29, v31, s[0:1]
	v_fma_f32 v29, -v33, v29, v25
	v_cmp_lt_f32_e64 s[0:1], 0, v29
	s_nop 1
	v_cndmask_b32_e64 v29, v31, v33, s[0:1]
	v_mul_f32_e32 v31, 0x37800000, v29
	v_cndmask_b32_e32 v29, v29, v31, vcc
	v_cmp_class_f32_e32 vcc, v25, v172
	s_nop 1
	v_cndmask_b32_e32 v25, v29, v25, vcc
	v_div_scale_f32 v29, s[0:1], v25, v25, 1.0
	v_rcp_f32_e32 v31, v29
	s_nop 0
	v_fma_f32 v33, -v29, v31, 1.0
	v_fmac_f32_e32 v31, v33, v31
	v_div_scale_f32 v33, vcc, 1.0, v25, 1.0
	v_mul_f32_e32 v36, v33, v31
	v_fma_f32 v39, -v29, v36, v33
	v_fmac_f32_e32 v36, v39, v31
	v_fma_f32 v29, -v29, v36, v33
	v_div_fmas_f32 v29, v29, v31, v36
	v_div_fixup_f32 v36, v29, v25, 1.0
	v_pk_mul_f32 v[250:251], v[250:251], v[36:37] op_sel_hi:[1,0]
	v_pk_mul_f32 v[252:253], v[252:253], v[36:37] op_sel_hi:[1,0]
	v_pk_mul_f32 v[250:251], v[0:1], v[250:251]
	v_pk_mul_f32 v[252:253], v[2:3], v[252:253]
	v_cvt_pk_bf16_f32 v250, v250, v251
	v_cvt_pk_bf16_f32 v251, v252, v253
	global_store_dwordx2 v[54:55], v[250:251], off
	v_pk_mul_f32 v[250:251], v[246:247], v[36:37] op_sel_hi:[1,0]
	v_pk_mul_f32 v[252:253], v[248:249], v[36:37] op_sel_hi:[1,0]
	v_pk_mul_f32 v[20:21], v[20:21], v[36:37] op_sel_hi:[1,0]
	v_pk_mul_f32 v[22:23], v[22:23], v[36:37] op_sel_hi:[1,0]
	v_pk_mul_f32 v[16:17], v[16:17], v[36:37] op_sel_hi:[1,0]
	v_pk_mul_f32 v[18:19], v[18:19], v[36:37] op_sel_hi:[1,0]
	v_pk_mul_f32 v[250:251], v[4:5], v[250:251]
	v_pk_mul_f32 v[252:253], v[6:7], v[252:253]
	v_mov_b32_e32 v29, v65
	v_pk_mul_f32 v[20:21], v[8:9], v[20:21]
	v_pk_mul_f32 v[22:23], v[10:11], v[22:23]
	v_mov_b32_e32 v31, v65
	v_pk_mul_f32 v[16:17], v[12:13], v[16:17]
	v_pk_mul_f32 v[18:19], v[14:15], v[18:19]
	v_mov_b32_e32 v33, v65
	v_cmp_lt_i32_e32 vcc, s46, v24
	v_cvt_pk_bf16_f32 v250, v250, v251
	v_cvt_pk_bf16_f32 v251, v252, v253
	v_lshl_add_u64 v[252:253], v[34:35], 0, v[28:29]
	v_cvt_pk_bf16_f32 v20, v20, v21
	v_cvt_pk_bf16_f32 v21, v22, v23
	v_lshl_add_u64 v[22:23], v[34:35], 0, v[30:31]
	v_cvt_pk_bf16_f32 v16, v16, v17
	v_cvt_pk_bf16_f32 v17, v18, v19
	v_lshl_add_u64 v[18:19], v[34:35], 0, v[32:33]
	s_or_b64 s[28:29], vcc, s[28:29]
	global_store_dwordx2 v[252:253], v[250:251], off
	global_store_dwordx2 v[22:23], v[20:21], off
	global_store_dwordx2 v[18:19], v[16:17], off
	s_andn2_b64 exec, exec, s[28:29]
	s_cbranch_execnz .LBB0_558

.LBB0_1027:
	v_lshlrev_b64 v[34:35], 2, v[24:25]
	v_lshlrev_b64 v[36:37], 2, v[26:27]
	v_lshlrev_b64 v[38:39], 2, v[28:29]
	v_lshlrev_b64 v[40:41], 2, v[30:31]
	s_add_i32 s0, s36, s37
	s_ashr_i32 s1, s0, 31
	s_lshl_b64 s[38:39], s[0:1], 14
	s_add_u32 s38, s86, s38
	s_addc_u32 s39, s87, s39
	s_lshl_b64 s[64:65], s[0:1], 8
	v_lshl_add_u64 v[46:47], s[38:39], 0, v[34:35]
	v_lshl_add_u64 v[50:51], s[38:39], 0, v[36:37]
	v_lshl_add_u64 v[52:53], s[38:39], 0, v[38:39]
	v_lshl_add_u64 v[54:55], s[38:39], 0, v[40:41]
	v_lshl_add_u64 v[56:57], v[32:33], 0, s[64:65]
	global_load_dword v200, v[46:47], off
	global_load_dword v201, v[46:47], off offset:256
	global_load_dword v202, v[50:51], off
	global_load_dword v203, v[46:47], off offset:768
	global_load_dword v204, v[52:53], off
	global_load_dword v205, v[46:47], off offset:1280
	global_load_dword v206, v[54:55], off
	global_load_dword v207, v[46:47], off offset:1792
	global_load_dwordx4 v[112:115], v[56:57], off
	global_load_dwordx4 v[116:119], v[56:57], off offset:16
	s_add_i32 s0, s0, 1
	s_ashr_i32 s1, s0, 31
	s_lshl_b64 s[38:39], s[0:1], 14
	s_add_u32 s38, s86, s38
	s_addc_u32 s39, s87, s39
	s_lshl_b64 s[64:65], s[0:1], 8
	v_lshl_add_u64 v[46:47], s[38:39], 0, v[34:35]
	v_lshl_add_u64 v[50:51], s[38:39], 0, v[36:37]
	v_lshl_add_u64 v[52:53], s[38:39], 0, v[38:39]
	v_lshl_add_u64 v[54:55], s[38:39], 0, v[40:41]
	v_lshl_add_u64 v[56:57], v[32:33], 0, s[64:65]
	global_load_dword v208, v[46:47], off
	global_load_dword v209, v[46:47], off offset:256
	global_load_dword v210, v[50:51], off
	global_load_dword v211, v[46:47], off offset:768
	global_load_dword v212, v[52:53], off
	global_load_dword v213, v[46:47], off offset:1280
	global_load_dword v214, v[54:55], off
	global_load_dword v215, v[46:47], off offset:1792
	global_load_dwordx4 v[120:123], v[56:57], off
	global_load_dwordx4 v[124:127], v[56:57], off offset:16
	s_add_i32 s0, s0, 1
	s_ashr_i32 s1, s0, 31
	s_lshl_b64 s[38:39], s[0:1], 14
	s_add_u32 s38, s86, s38
	s_addc_u32 s39, s87, s39
	s_lshl_b64 s[64:65], s[0:1], 8
	v_lshl_add_u64 v[46:47], s[38:39], 0, v[34:35]
	v_lshl_add_u64 v[50:51], s[38:39], 0, v[36:37]
	v_lshl_add_u64 v[52:53], s[38:39], 0, v[38:39]
	v_lshl_add_u64 v[54:55], s[38:39], 0, v[40:41]
	v_lshl_add_u64 v[56:57], v[32:33], 0, s[64:65]
	global_load_dword v216, v[46:47], off
	global_load_dword v217, v[46:47], off offset:256
	global_load_dword v218, v[50:51], off
	global_load_dword v219, v[46:47], off offset:768
	global_load_dword v220, v[52:53], off
	global_load_dword v221, v[46:47], off offset:1280
	global_load_dword v222, v[54:55], off
	global_load_dword v223, v[46:47], off offset:1792
	global_load_dwordx4 v[128:131], v[56:57], off
	global_load_dwordx4 v[132:135], v[56:57], off offset:16
	s_add_i32 s0, s0, 1
	s_ashr_i32 s1, s0, 31
	s_lshl_b64 s[38:39], s[0:1], 14
	s_add_u32 s38, s86, s38
	s_addc_u32 s39, s87, s39
	s_lshl_b64 s[64:65], s[0:1], 8
	v_lshl_add_u64 v[46:47], s[38:39], 0, v[34:35]
	v_lshl_add_u64 v[50:51], s[38:39], 0, v[36:37]
	v_lshl_add_u64 v[52:53], s[38:39], 0, v[38:39]
	v_lshl_add_u64 v[54:55], s[38:39], 0, v[40:41]
	v_lshl_add_u64 v[56:57], v[32:33], 0, s[64:65]
	global_load_dword v224, v[46:47], off
	global_load_dword v225, v[46:47], off offset:256
	global_load_dword v226, v[50:51], off
	global_load_dword v227, v[46:47], off offset:768
	global_load_dword v228, v[52:53], off
	global_load_dword v229, v[46:47], off offset:1280
	global_load_dword v230, v[54:55], off
	global_load_dword v231, v[46:47], off offset:1792
	global_load_dwordx4 v[136:139], v[56:57], off
	global_load_dwordx4 v[140:143], v[56:57], off offset:16
	s_waitcnt vmcnt(30)
	v_pk_fma_f32 v[8:9], v[8:9], v[112:113], v[200:201]
	v_pk_fma_f32 v[10:11], v[10:11], v[114:115], v[202:203]
	v_pk_fma_f32 v[12:13], v[12:13], v[116:117], v[204:205]
	v_pk_fma_f32 v[14:15], v[14:15], v[118:119], v[206:207]
	s_waitcnt vmcnt(20)
	v_pk_fma_f32 v[8:9], v[8:9], v[120:121], v[208:209]
	v_pk_fma_f32 v[10:11], v[10:11], v[122:123], v[210:211]
	v_pk_fma_f32 v[12:13], v[12:13], v[124:125], v[212:213]
	v_pk_fma_f32 v[14:15], v[14:15], v[126:127], v[214:215]
	s_waitcnt vmcnt(10)
	v_pk_fma_f32 v[8:9], v[8:9], v[128:129], v[216:217]
	v_pk_fma_f32 v[10:11], v[10:11], v[130:131], v[218:219]
	v_pk_fma_f32 v[12:13], v[12:13], v[132:133], v[220:221]
	v_pk_fma_f32 v[14:15], v[14:15], v[134:135], v[222:223]
	s_waitcnt vmcnt(0)
	v_pk_fma_f32 v[8:9], v[8:9], v[136:137], v[224:225]
	v_pk_fma_f32 v[10:11], v[10:11], v[138:139], v[226:227]
	v_pk_fma_f32 v[12:13], v[12:13], v[140:141], v[228:229]
	v_pk_fma_f32 v[14:15], v[14:15], v[142:143], v[230:231]
	s_add_i32 s37, s37, 4
	s_cmp_eq_u32 s31, s37
	s_cbranch_scc0 .LBB0_1027
	s_and_b32 s26, s26, 3
	s_cmp_eq_u32 s26, 0
	s_cbranch_scc0 .LBB0_1035
	s_branch .LBB0_1037

.LBB0_1036:
	s_cmp_eq_u32 s26, 1
	s_cbranch_scc1 .Lhp_r1
	s_cmp_eq_u32 s26, 2
	s_cbranch_scc1 .Lhp_r2
	v_lshlrev_b64 v[34:35], 2, v[24:25]
	v_lshlrev_b64 v[36:37], 2, v[26:27]
	v_lshlrev_b64 v[38:39], 2, v[28:29]
	v_lshlrev_b64 v[40:41], 2, v[30:31]
	s_ashr_i32 s1, s0, 31
	s_lshl_b64 s[30:31], s[0:1], 14
	s_add_u32 s30, s86, s30
	s_addc_u32 s31, s87, s31
	s_lshl_b64 s[36:37], s[0:1], 8
	v_lshl_add_u64 v[46:47], s[30:31], 0, v[34:35]
	v_lshl_add_u64 v[50:51], s[30:31], 0, v[36:37]
	v_lshl_add_u64 v[52:53], s[30:31], 0, v[38:39]
	v_lshl_add_u64 v[54:55], s[30:31], 0, v[40:41]
	v_lshl_add_u64 v[56:57], v[32:33], 0, s[36:37]
	global_load_dword v200, v[46:47], off
	global_load_dword v201, v[46:47], off offset:256
	global_load_dword v202, v[50:51], off
	global_load_dword v203, v[46:47], off offset:768
	global_load_dword v204, v[52:53], off
	global_load_dword v205, v[46:47], off offset:1280
	global_load_dword v206, v[54:55], off
	global_load_dword v207, v[46:47], off offset:1792
	global_load_dwordx4 v[112:115], v[56:57], off
	global_load_dwordx4 v[116:119], v[56:57], off offset:16
	s_add_i32 s0, s0, 1
	s_ashr_i32 s1, s0, 31
	s_lshl_b64 s[30:31], s[0:1], 14
	s_add_u32 s30, s86, s30
	s_addc_u32 s31, s87, s31
	s_lshl_b64 s[36:37], s[0:1], 8
	v_lshl_add_u64 v[46:47], s[30:31], 0, v[34:35]
	v_lshl_add_u64 v[50:51], s[30:31], 0, v[36:37]
	v_lshl_add_u64 v[52:53], s[30:31], 0, v[38:39]
	v_lshl_add_u64 v[54:55], s[30:31], 0, v[40:41]
	v_lshl_add_u64 v[56:57], v[32:33], 0, s[36:37]
	global_load_dword v208, v[46:47], off
	global_load_dword v209, v[46:47], off offset:256
	global_load_dword v210, v[50:51], off
	global_load_dword v211, v[46:47], off offset:768
	global_load_dword v212, v[52:53], off
	global_load_dword v213, v[46:47], off offset:1280
	global_load_dword v214, v[54:55], off
	global_load_dword v215, v[46:47], off offset:1792
	global_load_dwordx4 v[120:123], v[56:57], off
	global_load_dwordx4 v[124:127], v[56:57], off offset:16
	s_add_i32 s0, s0, 1
	s_ashr_i32 s1, s0, 31
	s_lshl_b64 s[30:31], s[0:1], 14
	s_add_u32 s30, s86, s30
	s_addc_u32 s31, s87, s31
	s_lshl_b64 s[36:37], s[0:1], 8
	v_lshl_add_u64 v[46:47], s[30:31], 0, v[34:35]
	v_lshl_add_u64 v[50:51], s[30:31], 0, v[36:37]
	v_lshl_add_u64 v[52:53], s[30:31], 0, v[38:39]
	v_lshl_add_u64 v[54:55], s[30:31], 0, v[40:41]
	v_lshl_add_u64 v[56:57], v[32:33], 0, s[36:37]
	global_load_dword v216, v[46:47], off
	global_load_dword v217, v[46:47], off offset:256
	global_load_dword v218, v[50:51], off
	global_load_dword v219, v[46:47], off offset:768
	global_load_dword v220, v[52:53], off
	global_load_dword v221, v[46:47], off offset:1280
	global_load_dword v222, v[54:55], off
	global_load_dword v223, v[46:47], off offset:1792
	global_load_dwordx4 v[128:131], v[56:57], off
	global_load_dwordx4 v[132:135], v[56:57], off offset:16
	s_waitcnt vmcnt(20)
	v_pk_fma_f32 v[8:9], v[8:9], v[112:113], v[200:201]
	v_pk_fma_f32 v[10:11], v[10:11], v[114:115], v[202:203]
	v_pk_fma_f32 v[12:13], v[12:13], v[116:117], v[204:205]
	v_pk_fma_f32 v[14:15], v[14:15], v[118:119], v[206:207]
	s_waitcnt vmcnt(10)
	v_pk_fma_f32 v[8:9], v[8:9], v[120:121], v[208:209]
	v_pk_fma_f32 v[10:11], v[10:11], v[122:123], v[210:211]
	v_pk_fma_f32 v[12:13], v[12:13], v[124:125], v[212:213]
	v_pk_fma_f32 v[14:15], v[14:15], v[126:127], v[214:215]
	s_waitcnt vmcnt(0)
	v_pk_fma_f32 v[8:9], v[8:9], v[128:129], v[216:217]
	v_pk_fma_f32 v[10:11], v[10:11], v[130:131], v[218:219]
	v_pk_fma_f32 v[12:13], v[12:13], v[132:133], v[220:221]
	v_pk_fma_f32 v[14:15], v[14:15], v[134:135], v[222:223]
	s_branch .LBB0_1037
.Lhp_r2:
	v_lshlrev_b64 v[34:35], 2, v[24:25]
	v_lshlrev_b64 v[36:37], 2, v[26:27]
	v_lshlrev_b64 v[38:39], 2, v[28:29]
	v_lshlrev_b64 v[40:41], 2, v[30:31]
	s_ashr_i32 s1, s0, 31
	s_lshl_b64 s[30:31], s[0:1], 14
	s_add_u32 s30, s86, s30
	s_addc_u32 s31, s87, s31
	s_lshl_b64 s[36:37], s[0:1], 8
	v_lshl_add_u64 v[46:47], s[30:31], 0, v[34:35]
	v_lshl_add_u64 v[50:51], s[30:31], 0, v[36:37]
	v_lshl_add_u64 v[52:53], s[30:31], 0, v[38:39]
	v_lshl_add_u64 v[54:55], s[30:31], 0, v[40:41]
	v_lshl_add_u64 v[56:57], v[32:33], 0, s[36:37]
	global_load_dword v200, v[46:47], off
	global_load_dword v201, v[46:47], off offset:256
	global_load_dword v202, v[50:51], off
	global_load_dword v203, v[46:47], off offset:768
	global_load_dword v204, v[52:53], off
	global_load_dword v205, v[46:47], off offset:1280
	global_load_dword v206, v[54:55], off
	global_load_dword v207, v[46:47], off offset:1792
	global_load_dwordx4 v[112:115], v[56:57], off
	global_load_dwordx4 v[116:119], v[56:57], off offset:16
	s_add_i32 s0, s0, 1
	s_ashr_i32 s1, s0, 31
	s_lshl_b64 s[30:31], s[0:1], 14
	s_add_u32 s30, s86, s30
	s_addc_u32 s31, s87, s31
	s_lshl_b64 s[36:37], s[0:1], 8
	v_lshl_add_u64 v[46:47], s[30:31], 0, v[34:35]
	v_lshl_add_u64 v[50:51], s[30:31], 0, v[36:37]
	v_lshl_add_u64 v[52:53], s[30:31], 0, v[38:39]
	v_lshl_add_u64 v[54:55], s[30:31], 0, v[40:41]
	v_lshl_add_u64 v[56:57], v[32:33], 0, s[36:37]
	global_load_dword v208, v[46:47], off
	global_load_dword v209, v[46:47], off offset:256
	global_load_dword v210, v[50:51], off
	global_load_dword v211, v[46:47], off offset:768
	global_load_dword v212, v[52:53], off
	global_load_dword v213, v[46:47], off offset:1280
	global_load_dword v214, v[54:55], off
	global_load_dword v215, v[46:47], off offset:1792
	global_load_dwordx4 v[120:123], v[56:57], off
	global_load_dwordx4 v[124:127], v[56:57], off offset:16
	s_waitcnt vmcnt(10)
	v_pk_fma_f32 v[8:9], v[8:9], v[112:113], v[200:201]
	v_pk_fma_f32 v[10:11], v[10:11], v[114:115], v[202:203]
	v_pk_fma_f32 v[12:13], v[12:13], v[116:117], v[204:205]
	v_pk_fma_f32 v[14:15], v[14:15], v[118:119], v[206:207]
	s_waitcnt vmcnt(0)
	v_pk_fma_f32 v[8:9], v[8:9], v[120:121], v[208:209]
	v_pk_fma_f32 v[10:11], v[10:11], v[122:123], v[210:211]
	v_pk_fma_f32 v[12:13], v[12:13], v[124:125], v[212:213]
	v_pk_fma_f32 v[14:15], v[14:15], v[126:127], v[214:215]
	s_branch .LBB0_1037
.Lhp_r1:
	v_lshlrev_b64 v[34:35], 2, v[24:25]
	v_lshlrev_b64 v[36:37], 2, v[26:27]
	v_lshlrev_b64 v[38:39], 2, v[28:29]
	v_lshlrev_b64 v[40:41], 2, v[30:31]
	s_ashr_i32 s1, s0, 31
	s_lshl_b64 s[30:31], s[0:1], 14
	s_add_u32 s30, s86, s30
	s_addc_u32 s31, s87, s31
	s_lshl_b64 s[36:37], s[0:1], 8
	v_lshl_add_u64 v[46:47], s[30:31], 0, v[34:35]
	v_lshl_add_u64 v[50:51], s[30:31], 0, v[36:37]
	v_lshl_add_u64 v[52:53], s[30:31], 0, v[38:39]
	v_lshl_add_u64 v[54:55], s[30:31], 0, v[40:41]
	v_lshl_add_u64 v[56:57], v[32:33], 0, s[36:37]
	global_load_dword v200, v[46:47], off
	global_load_dword v201, v[46:47], off offset:256
	global_load_dword v202, v[50:51], off
	global_load_dword v203, v[46:47], off offset:768
	global_load_dword v204, v[52:53], off
	global_load_dword v205, v[46:47], off offset:1280
	global_load_dword v206, v[54:55], off
	global_load_dword v207, v[46:47], off offset:1792
	global_load_dwordx4 v[112:115], v[56:57], off
	global_load_dwordx4 v[116:119], v[56:57], off offset:16
	s_waitcnt vmcnt(0)
	v_pk_fma_f32 v[8:9], v[8:9], v[112:113], v[200:201]
	v_pk_fma_f32 v[10:11], v[10:11], v[114:115], v[202:203]
	v_pk_fma_f32 v[12:13], v[12:13], v[116:117], v[204:205]
	v_pk_fma_f32 v[14:15], v[14:15], v[118:119], v[206:207]
